# attA loop: every packed v_pk_add_f32 (exponent offsets, row sums) between the MFMAs split into two scalar v_add_f32
# speedup vs baseline: 1.0114x; 1.0069x over previous
; #define LAS __attribute__((address_space(3)))
; __device__ __forceinline__ int crow(int r, int hi) { return (r & 3) + 8 * (r >> 2) + 4 * hi; }
; __device__ __forceinline__ void unit(LAS unsigned char* lds, bf16_t* P1, const bf16_t* vaT, int b, int h, int qblk, float lam, const float* subln_w, const float* khalf) {
;     ...
;         if (jj + 2 < NT) asm volatile("s_waitcnt vmcnt(8) lgkmcnt(0)\n\ts_barrier" ::: "memory"); else if (jj + 1 < NT) asm volatile("s_waitcnt vmcnt(4) lgkmcnt(0)\n\ts_barrier" ::: "memory"); else asm volatile("s_waitcnt vmcnt(0) lgkmcnt(0)\n\ts_barrier" ::: "memory");
;         { typedef int i32x4 __attribute__((ext_vector_type(4)));
;           const i32x4 fa = *(const LAS i32x4*)(lds + 4 * STG + (jj & 1) * 32), fb = *(const LAS i32x4*)(lds + 4 * STG + (jj & 1) * 32 + 16);
;           if (((fa[0] + fa[1]) + (fa[2] + fa[3])) + ((fb[0] + fb[1]) + (fb[2] + fb[3])) == 8) break; }
;         if (jj + 3 < NT) { DMA_TILE(j - 3, (stg + 3) & 3); }
;         const LAS unsigned char* kb = lds + stg * STG;
;         stg = (stg + 1) & 3;
;         f32x16 S0, S1;
;         { float slv = sl2; asm volatile("" : "+v"(slv));
; #pragma unroll
;           for (int r = 0; r < 16; ++r) { S0[r] = __builtin_fmaf(slv, (float)((r & 3) + 8 * (r >> 2)), sl2h); S1[r] = S0[r]; } }
; #pragma unroll
;         for (int ks = 0; ks < 4; ++ks) {
;             const bf16x8 a0 = *(const LAS bf16x8*)(kb + koff[ks]);
;             const bf16x8 a1 = *(const LAS bf16x8*)(kb + koff[ks] + 32 * 256);
;             S0 = MFMA32(a0, qf[ks], S0); S1 = MFMA32(a1, qf[ks], S1);
;         }
;         const int kv0 = 64 * j;
;         if (j >= NT - 2) {
; #pragma unroll
;             for (int r = 0; r < 16; ++r) { const int kv = kv0 + crow(r, hi); if (kv > qrow) S0[r] = -INFINITY; if (kv + 32 > qrow) S1[r] = -INFINITY; }
;         }
;         const float tb0 = sl2 * (float)(kv0 - qrow), tb1 = tb0 + sl2 * 32.f;
;         float mx0 = S0[0], mx1 = S1[0];
; #pragma unroll
;         for (int r = 1; r < 16; ++r) { mx0 = fmaxf(mx0, S0[r]); mx1 = fmaxf(mx1, S1[r]); }
;         float mt = fmaxf(mx0 + tb0, mx1 + tb1); mt = fmaxf(mt, __shfl_xor(mt, 32));
;         const bool skip = __all((mt < m - 24.f) || (mt == -INFINITY));
;         if (!skip) {
;         const float mn = fmaxf(m, mt); const float alpha = ex2(m - mn); m = mn;
.La_after_bar0:
	s_lshl_b32 s82, s80, 15
	s_add_i32 s83, s82, 0x8000
	s_sub_i32 s100, s76, 64
	s_and_b32 s2, s81, 2
	s_lshl_b32 s2, s2, 4
	s_add_i32 s2, s2, 0x20000
	v_mov_b32_e32 v70, s2
	ds_read_b128 v[66:69], v70
	ds_read_b128 v[70:73], v70 offset:16
	v_add3_u32 v201, s82, v129, v151
	v_add3_u32 v135, s82, v185, v151
	v_add3_u32 v249, s82, v186, v151
	v_add3_u32 v254, s82, v187, v151
	ds_read_b128 v[192:195], v201
	ds_read_b128 v[202:205], v135
	ds_read_b128 v[210:213], v249
	ds_read_b128 v[218:221], v254
	ds_read_b128 v[196:199], v201 offset:8192
	ds_read_b128 v[206:209], v135 offset:8192
	ds_read_b128 v[214:217], v249 offset:8192
	ds_read_b128 v[222:225], v254 offset:8192
	s_waitcnt lgkmcnt(8)
	v_add3_u32 v66, v66, v67, v68
	v_add3_u32 v69, v69, v70, v71
	v_add_u32_e32 v72, v72, v73
	v_add3_u32 v66, v66, v69, v72
	v_cmp_eq_u32_e32 vcc, 8, v66
	s_cbranch_vccnz .LBB0_420
	s_waitcnt lgkmcnt(4)
	v_mfma_f32_32x32x16_bf16 v[82:97], v[192:195], v[98:101], v[226:241]
	v_add_u32_e32 v244, s82, v168
	v_add_u32_e32 v245, s82, v169
	v_add_u32_e32 v246, s82, v170
	v_mfma_f32_32x32x16_bf16 v[82:97], v[202:205], v[102:105], v[82:97]
	v_add_u32_e32 v247, s82, v171
	v_add_f32_e32 v143, v133, v121
	v_fma_f32 v251, v127, v137, v188
	v_mfma_f32_32x32x16_bf16 v[82:97], v[210:213], v[106:109], v[82:97]
	v_fma_f32 v142, v127, v137, -v132
	v_max_f32_e32 v143, 0xff7fffff, v143
	v_add_f32_e32 v248, v142, v188
	v_mfma_f32_32x32x16_bf16 v[82:97], v[218:221], v[110:113], v[82:97]
	ds_read_b128 v[192:195], v244 offset:16384
	ds_read_b128 v[202:205], v244 offset:20480
	ds_read_b128 v[210:213], v244 offset:24576
	ds_read_b128 v[218:221], v244 offset:28672
	s_waitcnt lgkmcnt(4)
	v_mfma_f32_32x32x16_bf16 v[66:81], v[196:199], v[98:101], v[226:241]
	v_mfma_f32_32x32x16_bf16 v[66:81], v[206:209], v[102:105], v[66:81]
	v_max3_f32 v0, v82, v83, v84
	v_max3_f32 v0, v0, v85, v86
	v_mfma_f32_32x32x16_bf16 v[66:81], v[214:217], v[106:109], v[66:81]
	v_max3_f32 v0, v0, v87, v88
	v_max3_f32 v0, v0, v89, v90
	v_max3_f32 v0, v0, v91, v92
	v_mfma_f32_32x32x16_bf16 v[66:81], v[222:225], v[110:113], v[66:81]
	v_max3_f32 v0, v0, v93, v94
	v_max3_f32 v0, v0, v95, v96
	v_max_f32_e32 v0, v0, v97
	ds_read_b128 v[196:199], v245 offset:16384
	ds_read_b128 v[206:209], v245 offset:20480
	ds_read_b128 v[214:217], v245 offset:24576
	ds_read_b128 v[222:225], v245 offset:28672
	s_nop 3
	v_add_u32_e32 v243, s76, v189
	v_add_u32_e32 v130, 0x60, v243
	v_add_u32_e32 v131, 64, v243
	v_cmp_le_i32_e32 vcc, v130, v125
	s_nop 6
	v_cndmask_b32_e32 v66, v184, v66, vcc
	v_cmp_lt_i32_e32 vcc, v131, v125
	s_nop 1
	v_cndmask_b32_e32 v83, v184, v83, vcc
	v_cmp_le_i32_e32 vcc, v131, v125
	v_add_u32_e32 v131, 0x61, v243
	s_nop 0
	v_cndmask_b32_e32 v82, v184, v82, vcc
	v_cmp_le_i32_e32 vcc, v131, v125
	v_add_u32_e32 v131, 0x42, v243
	s_nop 0
	v_cndmask_b32_e32 v67, v184, v67, vcc
	v_cmp_le_i32_e32 vcc, v131, v125
	v_add_u32_e32 v131, 0x62, v243
	s_nop 0
	v_cndmask_b32_e32 v84, v184, v84, vcc
	v_cmp_le_i32_e32 vcc, v131, v125
	v_add_u32_e32 v131, 0x43, v243
	s_nop 0
	v_cndmask_b32_e32 v68, v184, v68, vcc
	v_cmp_le_i32_e32 vcc, v131, v125
	v_add_u32_e32 v131, 0x63, v243
	s_nop 0
	v_cndmask_b32_e32 v85, v184, v85, vcc
	v_cmp_le_i32_e32 vcc, v131, v125
	v_add_u32_e32 v131, 0x48, v243
	s_nop 0
	v_cndmask_b32_e32 v69, v184, v69, vcc
	v_cmp_le_i32_e32 vcc, v131, v125
	v_add_u32_e32 v131, 0x68, v243
	s_nop 0
	v_cndmask_b32_e32 v86, v184, v86, vcc
	v_cmp_le_i32_e32 vcc, v131, v125
	v_add_u32_e32 v131, 0x49, v243
	s_nop 0
	v_cndmask_b32_e32 v70, v184, v70, vcc
	v_cmp_le_i32_e32 vcc, v131, v125
	v_add_u32_e32 v131, 0x69, v243
	s_nop 0
	v_cndmask_b32_e32 v87, v184, v87, vcc
	v_cmp_le_i32_e32 vcc, v131, v125
	v_add_u32_e32 v131, 0x4a, v243
	s_nop 0
	v_cndmask_b32_e32 v71, v184, v71, vcc
	v_cmp_le_i32_e32 vcc, v131, v125
	v_add_u32_e32 v131, 0x6a, v243
	s_nop 0
	v_cndmask_b32_e32 v88, v184, v88, vcc
	v_cmp_le_i32_e32 vcc, v131, v125
	v_add_u32_e32 v131, 0x4b, v243
	s_nop 0
	v_cndmask_b32_e32 v72, v184, v72, vcc
	v_cmp_le_i32_e32 vcc, v131, v125
	v_add_u32_e32 v131, 0x6b, v243
	s_nop 0
	v_cndmask_b32_e32 v89, v184, v89, vcc
	v_cmp_le_i32_e32 vcc, v131, v125
	v_add_u32_e32 v131, 0x50, v243
	s_nop 0
	v_cndmask_b32_e32 v73, v184, v73, vcc
	v_cmp_le_i32_e32 vcc, v131, v125
	v_add_u32_e32 v131, 0x70, v243
	s_nop 0
	v_cndmask_b32_e32 v90, v184, v90, vcc
	v_cmp_le_i32_e32 vcc, v131, v125
	v_add_u32_e32 v131, 0x51, v243
	s_nop 0
	v_cndmask_b32_e32 v74, v184, v74, vcc
	v_cmp_le_i32_e32 vcc, v131, v125
	v_add_u32_e32 v131, 0x71, v243
	s_nop 0
	v_cndmask_b32_e32 v91, v184, v91, vcc
	v_cmp_le_i32_e32 vcc, v131, v125
	v_add_u32_e32 v131, 0x52, v243
	s_nop 0
	v_cndmask_b32_e32 v75, v184, v75, vcc
	v_cmp_le_i32_e32 vcc, v131, v125
	v_add_u32_e32 v131, 0x72, v243
	s_nop 0
	v_cndmask_b32_e32 v92, v184, v92, vcc
	v_cmp_le_i32_e32 vcc, v131, v125
	v_add_u32_e32 v131, 0x53, v243
	s_nop 0
	v_cndmask_b32_e32 v76, v184, v76, vcc
	v_cmp_le_i32_e32 vcc, v131, v125
	v_add_u32_e32 v131, 0x73, v243
	s_nop 0
	v_cndmask_b32_e32 v93, v184, v93, vcc
	v_cmp_le_i32_e32 vcc, v131, v125
	v_add_u32_e32 v131, 0x58, v243
	s_nop 0
	v_cndmask_b32_e32 v77, v184, v77, vcc
	v_cmp_le_i32_e32 vcc, v131, v125
	v_add_u32_e32 v131, 0x78, v243
	s_nop 0
	v_cndmask_b32_e32 v94, v184, v94, vcc
	v_cmp_le_i32_e32 vcc, v131, v125
	v_add_u32_e32 v131, 0x59, v243
	s_nop 0
	v_cndmask_b32_e32 v78, v184, v78, vcc
	v_cmp_le_i32_e32 vcc, v131, v125
	v_add_u32_e32 v131, 0x79, v243
	s_nop 0
	v_cndmask_b32_e32 v95, v184, v95, vcc
	v_cmp_le_i32_e32 vcc, v131, v125
	v_add_u32_e32 v131, 0x5a, v243
	s_nop 0
	v_cndmask_b32_e32 v79, v184, v79, vcc
	v_cmp_le_i32_e32 vcc, v131, v125
	v_add_u32_e32 v131, 0x7a, v243
	s_nop 0
	v_cndmask_b32_e32 v96, v184, v96, vcc
	v_cmp_le_i32_e32 vcc, v131, v125
	v_add_u32_e32 v131, 0x5b, v243
	v_add_u32_e32 v243, 0x7b, v243
	v_cndmask_b32_e32 v80, v184, v80, vcc
	v_cmp_le_i32_e32 vcc, v131, v125
	s_nop 1
	v_cndmask_b32_e32 v97, v184, v97, vcc
	v_cmp_le_i32_e32 vcc, v243, v125
	s_nop 1
	v_cndmask_b32_e32 v81, v184, v81, vcc
	v_max3_f32 v0, v82, v83, v84
	v_max3_f32 v0, v0, v85, v86
	v_max3_f32 v0, v0, v87, v88
	v_max3_f32 v0, v0, v89, v90
	v_max3_f32 v0, v0, v91, v92
	v_max3_f32 v0, v0, v93, v94
	v_max3_f32 v0, v0, v95, v96
	v_max_f32_e32 v0, v0, v97
	v_fmac_f32_e32 v0, v127, v137
	s_nop 1
	v_max3_f32 v120, v66, v67, v68
	v_max3_f32 v120, v120, v69, v70
	v_max3_f32 v120, v120, v71, v72
	v_max3_f32 v120, v120, v73, v74
	v_max3_f32 v120, v120, v75, v76
	v_max3_f32 v120, v120, v77, v78
	v_max3_f32 v120, v120, v79, v80
	v_max_f32_e32 v120, v120, v81
	v_add_f32_e32 v120, v251, v120
	v_max_f32_e32 v0, v0, v120
	v_mov_b32_e32 v120, v0
	s_nop 1
	v_permlane32_swap_b32_e32 v0, v120
	v_max_f32_e32 v0, v0, v120
	v_cmp_lt_f32_e32 vcc, v0, v143
	v_max_f32_e32 v133, v133, v0
	v_mov_b32_e32 v255, v0
	s_andn2_b64 s[2:3], exec, vcc
	s_cbranch_scc0 .La_endA0
; #define LAS __attribute__((address_space(3)))
; __device__ __forceinline__ unsigned cvtpk(float lo, float hi) { return pg8::cvt_pk_bf16(lo, hi); }
; __device__ __forceinline__ float ex2(float v) { return __builtin_amdgcn_exp2f(v); }
; #define MFMA32(a, b, c) __builtin_amdgcn_mfma_f32_32x32x16_bf16((a), (b), (c), 0, 0, 0)
; __device__ __forceinline__ void unit(LAS unsigned char* lds, bf16_t* P1, const bf16_t* vaT, int b, int h, int qblk, float lam, const float* subln_w, const float* khalf) {
;     ...
;         const float mn = fmaxf(m, mt); const float alpha = ex2(m - mn); m = mn;
;         const float c0 = tb0 - mn, c1 = tb1 - mn;
;         f32x2 ps2 = (f32x2){0.f, 0.f};
; #pragma unroll
;         for (int r = 0; r < 16; r += 2) { f32x2 a = (f32x2){S0[r], S0[r + 1]} + c0, bq = (f32x2){S1[r], S1[r + 1]} + c1;
;             a.x = ex2(a.x); a.y = ex2(a.y); bq.x = ex2(bq.x); bq.y = ex2(bq.y); S0[r] = a.x; S0[r + 1] = a.y; S1[r] = bq.x; S1[r + 1] = bq.y; ps2 = ps2 + a; ps2 = ps2 + bq; }
;         l = l * alpha + (ps2.x + ps2.y);
;         if (__any(alpha != 1.f)) {
; #pragma unroll
;             for (int d = 0; d < 4; ++d) O[d] = O[d] * alpha;
;         }
;         u32x4 pk[2][2];
; #pragma unroll
;         for (int s = 0; s < 2; ++s) {
;             pk[0][s] = (u32x4){cvtpk(S0[8 * s + 0], S0[8 * s + 1]), cvtpk(S0[8 * s + 2], S0[8 * s + 3]), cvtpk(S0[8 * s + 4], S0[8 * s + 5]), cvtpk(S0[8 * s + 6], S0[8 * s + 7])};
;             pk[1][s] = (u32x4){cvtpk(S1[8 * s + 0], S1[8 * s + 1]), cvtpk(S1[8 * s + 2], S1[8 * s + 3]), cvtpk(S1[8 * s + 4], S1[8 * s + 5]), cvtpk(S1[8 * s + 6], S1[8 * s + 7])};
;         }
; #pragma unroll
;         for (int d = 0; d < 4; ++d)
; #pragma unroll
;             for (int t2 = 0; t2 < 2; ++t2)
; #pragma unroll
;                 for (int s = 0; s < 2; ++s) {
;                     const bf16x8 vf = *(const LAS bf16x8*)(kb + voff[2 * t2 + s] + d * 32 * 128);
;                     O[d] = MFMA32(vf, __builtin_bit_cast(bf16x8, pk[t2][s]), O[d]);
;                 }
;         }
	v_add_f32_e32 v82, v142, v82
	v_add_f32_e32 v83, v142, v83
	v_add_f32_e32 v84, v142, v84
	v_add_f32_e32 v85, v142, v85
	v_add_f32_e32 v86, v142, v86
	v_add_f32_e32 v87, v142, v87
	v_add_f32_e32 v88, v142, v88
	v_add_f32_e32 v89, v142, v89
	v_exp_f32_e32 v82, v82
	v_exp_f32_e32 v83, v83
	v_exp_f32_e32 v84, v84
	v_exp_f32_e32 v85, v85
	v_exp_f32_e32 v86, v86
	v_exp_f32_e32 v87, v87
	v_exp_f32_e32 v88, v88
	v_exp_f32_e32 v89, v89
	v_add_f32_e32 v252, v82, v84
	v_add_f32_e32 v253, v83, v85
	v_cvt_pk_bf16_f32 v82, v82, v83
	v_cvt_pk_bf16_f32 v83, v84, v85
	v_cvt_pk_bf16_f32 v84, v86, v87
	v_cvt_pk_bf16_f32 v85, v88, v89
	v_add_f32_e32 v252, v252, v86
	v_add_f32_e32 v253, v253, v87
	v_add_f32_e32 v252, v252, v88
	v_add_f32_e32 v253, v253, v89
	s_waitcnt lgkmcnt(4)
	v_mfma_f32_32x32x16_bf16 v[50:65], v[192:195], v[82:85], v[50:65]
	ds_read_b128 v[192:195], v246 offset:16384
	v_add_f32_e32 v90, v142, v90
	v_add_f32_e32 v91, v142, v91
	v_add_f32_e32 v92, v142, v92
	v_add_f32_e32 v93, v142, v93
	v_add_f32_e32 v94, v142, v94
	v_add_f32_e32 v95, v142, v95
	v_add_f32_e32 v96, v142, v96
	v_mfma_f32_32x32x16_bf16 v[34:49], v[202:205], v[82:85], v[34:49]
	ds_read_b128 v[202:205], v246 offset:20480
	v_add_f32_e32 v97, v142, v97
	v_exp_f32_e32 v90, v90
	v_exp_f32_e32 v91, v91
	v_exp_f32_e32 v92, v92
	v_exp_f32_e32 v93, v93
	v_exp_f32_e32 v94, v94
	v_exp_f32_e32 v95, v95
	v_mfma_f32_32x32x16_bf16 v[18:33], v[210:213], v[82:85], v[18:33]
	ds_read_b128 v[210:213], v246 offset:24576
	v_exp_f32_e32 v96, v96
	v_exp_f32_e32 v97, v97
	v_add_f32_e32 v252, v252, v90
	v_add_f32_e32 v253, v253, v91
	v_add_f32_e32 v252, v252, v92
	v_add_f32_e32 v253, v253, v93
	v_cvt_pk_bf16_f32 v90, v90, v91
	v_mfma_f32_32x32x16_bf16 v[2:17], v[218:221], v[82:85], v[2:17]
	ds_read_b128 v[218:221], v246 offset:28672
	v_cvt_pk_bf16_f32 v91, v92, v93
	v_cvt_pk_bf16_f32 v92, v94, v95
	v_cvt_pk_bf16_f32 v93, v96, v97
	v_add_f32_e32 v252, v252, v94
	v_add_f32_e32 v253, v253, v95
	v_add_f32_e32 v252, v252, v96
	v_add_f32_e32 v253, v253, v97
	s_waitcnt lgkmcnt(4)
	v_mfma_f32_32x32x16_bf16 v[50:65], v[196:199], v[90:93], v[50:65]
	ds_read_b128 v[196:199], v247 offset:16384
	v_add_f32_e32 v66, v248, v66
	v_add_f32_e32 v67, v248, v67
	v_add_f32_e32 v68, v248, v68
	v_add_f32_e32 v69, v248, v69
	v_add_f32_e32 v70, v248, v70
	v_add_f32_e32 v71, v248, v71
	v_add_f32_e32 v72, v248, v72
	v_mfma_f32_32x32x16_bf16 v[34:49], v[206:209], v[90:93], v[34:49]
	ds_read_b128 v[206:209], v247 offset:20480
	v_add_f32_e32 v73, v248, v73
	v_exp_f32_e32 v66, v66
	v_exp_f32_e32 v67, v67
	v_exp_f32_e32 v68, v68
	v_exp_f32_e32 v69, v69
	v_exp_f32_e32 v70, v70
	v_exp_f32_e32 v71, v71
	v_mfma_f32_32x32x16_bf16 v[18:33], v[214:217], v[90:93], v[18:33]
	ds_read_b128 v[214:217], v247 offset:24576
	v_exp_f32_e32 v72, v72
	v_exp_f32_e32 v73, v73
	v_add_f32_e32 v252, v252, v66
	v_add_f32_e32 v253, v253, v67
	v_add_f32_e32 v252, v252, v68
	v_add_f32_e32 v253, v253, v69
	v_cvt_pk_bf16_f32 v66, v66, v67
	v_mfma_f32_32x32x16_bf16 v[2:17], v[222:225], v[90:93], v[2:17]
	ds_read_b128 v[222:225], v247 offset:28672
	v_cvt_pk_bf16_f32 v67, v68, v69
	v_cvt_pk_bf16_f32 v68, v70, v71
	v_cvt_pk_bf16_f32 v69, v72, v73
	v_add_f32_e32 v252, v252, v70
	v_add_f32_e32 v253, v253, v71
	v_add_f32_e32 v252, v252, v72
	v_add_f32_e32 v253, v253, v73
	s_waitcnt lgkmcnt(4)
	v_mfma_f32_32x32x16_bf16 v[50:65], v[192:195], v[66:69], v[50:65]
	v_add_f32_e32 v74, v248, v74
	v_add_f32_e32 v75, v248, v75
	v_add_f32_e32 v76, v248, v76
	v_add_f32_e32 v77, v248, v77
	v_add_f32_e32 v78, v248, v78
	v_add_f32_e32 v79, v248, v79
	v_add_f32_e32 v80, v248, v80
	v_mfma_f32_32x32x16_bf16 v[34:49], v[202:205], v[66:69], v[34:49]
	v_add_f32_e32 v81, v248, v81
	v_exp_f32_e32 v74, v74
	v_exp_f32_e32 v75, v75
	v_exp_f32_e32 v76, v76
	v_exp_f32_e32 v77, v77
	v_exp_f32_e32 v78, v78
	v_exp_f32_e32 v79, v79
	v_mfma_f32_32x32x16_bf16 v[18:33], v[210:213], v[66:69], v[18:33]
	v_exp_f32_e32 v80, v80
	v_exp_f32_e32 v81, v81
	v_add_f32_e32 v252, v252, v74
	v_add_f32_e32 v253, v253, v75
	v_add_f32_e32 v252, v252, v76
	v_add_f32_e32 v253, v253, v77
	v_cvt_pk_bf16_f32 v74, v74, v75
	v_mfma_f32_32x32x16_bf16 v[2:17], v[218:221], v[66:69], v[2:17]
	v_cvt_pk_bf16_f32 v75, v76, v77
	v_cvt_pk_bf16_f32 v76, v78, v79
	v_cvt_pk_bf16_f32 v77, v80, v81
	v_add_f32_e32 v252, v252, v78
	v_add_f32_e32 v253, v253, v79
	v_add_f32_e32 v252, v252, v80
	v_add_f32_e32 v253, v253, v81
	s_waitcnt lgkmcnt(0)
	v_mfma_f32_32x32x16_bf16 v[50:65], v[196:199], v[74:77], v[50:65]
	v_add_f32_e32 v250, v252, v253
	v_mfma_f32_32x32x16_bf16 v[34:49], v[206:209], v[74:77], v[34:49]
	v_add_f32_e32 v191, v191, v250
	v_mfma_f32_32x32x16_bf16 v[18:33], v[214:217], v[74:77], v[18:33]
	v_mfma_f32_32x32x16_bf16 v[2:17], v[222:225], v[74:77], v[2:17]

; __device__ __forceinline__ int crow(int r, int hi) { return (r & 3) + 8 * (r >> 2) + 4 * hi; }
; __device__ __forceinline__ float ex2(float v) { return __builtin_amdgcn_exp2f(v); }
; __device__ __forceinline__ void unit(LAS unsigned char* lds, bf16_t* P1, const bf16_t* vaT, int b, int h, int qblk, float lam, const float* subln_w, const float* khalf) {
;     ...
;         const int kv0 = 64 * j;
;         if (j >= NT - 2) {
; #pragma unroll
;             for (int r = 0; r < 16; ++r) { const int kv = kv0 + crow(r, hi); if (kv > qrow) S0[r] = -INFINITY; if (kv + 32 > qrow) S1[r] = -INFINITY; }
;         }
;         const float tb0 = sl2 * (float)(kv0 - qrow), tb1 = tb0 + sl2 * 32.f;
;         float mx0 = S0[0], mx1 = S1[0];
; #pragma unroll
;         for (int r = 1; r < 16; ++r) { mx0 = fmaxf(mx0, S0[r]); mx1 = fmaxf(mx1, S1[r]); }
;         float mt = fmaxf(mx0 + tb0, mx1 + tb1); mt = fmaxf(mt, __shfl_xor(mt, 32));
;         const bool skip = __all((mt < m - 24.f) || (mt == -INFINITY));
;         if (!skip) {
;         const float mn = fmaxf(m, mt); const float alpha = ex2(m - mn); m = mn;
.La_qk_doneB0:
	ds_read_b128 v[196:199], v245 offset:49152
	ds_read_b128 v[206:209], v245 offset:53248
	ds_read_b128 v[214:217], v245 offset:57344
	ds_read_b128 v[222:225], v245 offset:61440
	s_nop 3
	v_add_u32_e32 v243, s100, v189
	v_add_u32_e32 v130, 0x60, v243
	v_add_u32_e32 v131, 64, v243
	v_cmp_le_i32_e32 vcc, v130, v125
	s_nop 6
	v_cndmask_b32_e32 v66, v184, v66, vcc
	v_cmp_lt_i32_e32 vcc, v131, v125
	s_nop 1
	v_cndmask_b32_e32 v83, v184, v83, vcc
	v_cmp_le_i32_e32 vcc, v131, v125
	v_add_u32_e32 v131, 0x61, v243
	s_nop 0
	v_cndmask_b32_e32 v82, v184, v82, vcc
	v_cmp_le_i32_e32 vcc, v131, v125
	v_add_u32_e32 v131, 0x42, v243
	s_nop 0
	v_cndmask_b32_e32 v67, v184, v67, vcc
	v_cmp_le_i32_e32 vcc, v131, v125
	v_add_u32_e32 v131, 0x62, v243
	s_nop 0
	v_cndmask_b32_e32 v84, v184, v84, vcc
	v_cmp_le_i32_e32 vcc, v131, v125
	v_add_u32_e32 v131, 0x43, v243
	s_nop 0
	v_cndmask_b32_e32 v68, v184, v68, vcc
	v_cmp_le_i32_e32 vcc, v131, v125
	v_add_u32_e32 v131, 0x63, v243
	s_nop 0
	v_cndmask_b32_e32 v85, v184, v85, vcc
	v_cmp_le_i32_e32 vcc, v131, v125
	v_add_u32_e32 v131, 0x48, v243
	s_nop 0
	v_cndmask_b32_e32 v69, v184, v69, vcc
	v_cmp_le_i32_e32 vcc, v131, v125
	v_add_u32_e32 v131, 0x68, v243
	s_nop 0
	v_cndmask_b32_e32 v86, v184, v86, vcc
	v_cmp_le_i32_e32 vcc, v131, v125
	v_add_u32_e32 v131, 0x49, v243
	s_nop 0
	v_cndmask_b32_e32 v70, v184, v70, vcc
	v_cmp_le_i32_e32 vcc, v131, v125
	v_add_u32_e32 v131, 0x69, v243
	s_nop 0
	v_cndmask_b32_e32 v87, v184, v87, vcc
	v_cmp_le_i32_e32 vcc, v131, v125
	v_add_u32_e32 v131, 0x4a, v243
	s_nop 0
	v_cndmask_b32_e32 v71, v184, v71, vcc
	v_cmp_le_i32_e32 vcc, v131, v125
	v_add_u32_e32 v131, 0x6a, v243
	s_nop 0
	v_cndmask_b32_e32 v88, v184, v88, vcc
	v_cmp_le_i32_e32 vcc, v131, v125
	v_add_u32_e32 v131, 0x4b, v243
	s_nop 0
	v_cndmask_b32_e32 v72, v184, v72, vcc
	v_cmp_le_i32_e32 vcc, v131, v125
	v_add_u32_e32 v131, 0x6b, v243
	s_nop 0
	v_cndmask_b32_e32 v89, v184, v89, vcc
	v_cmp_le_i32_e32 vcc, v131, v125
	v_add_u32_e32 v131, 0x50, v243
	s_nop 0
	v_cndmask_b32_e32 v73, v184, v73, vcc
	v_cmp_le_i32_e32 vcc, v131, v125
	v_add_u32_e32 v131, 0x70, v243
	s_nop 0
	v_cndmask_b32_e32 v90, v184, v90, vcc
	v_cmp_le_i32_e32 vcc, v131, v125
	v_add_u32_e32 v131, 0x51, v243
	s_nop 0
	v_cndmask_b32_e32 v74, v184, v74, vcc
	v_cmp_le_i32_e32 vcc, v131, v125
	v_add_u32_e32 v131, 0x71, v243
	s_nop 0
	v_cndmask_b32_e32 v91, v184, v91, vcc
	v_cmp_le_i32_e32 vcc, v131, v125
	v_add_u32_e32 v131, 0x52, v243
	s_nop 0
	v_cndmask_b32_e32 v75, v184, v75, vcc
	v_cmp_le_i32_e32 vcc, v131, v125
	v_add_u32_e32 v131, 0x72, v243
	s_nop 0
	v_cndmask_b32_e32 v92, v184, v92, vcc
	v_cmp_le_i32_e32 vcc, v131, v125
	v_add_u32_e32 v131, 0x53, v243
	s_nop 0
	v_cndmask_b32_e32 v76, v184, v76, vcc
	v_cmp_le_i32_e32 vcc, v131, v125
	v_add_u32_e32 v131, 0x73, v243
	s_nop 0
	v_cndmask_b32_e32 v93, v184, v93, vcc
	v_cmp_le_i32_e32 vcc, v131, v125
	v_add_u32_e32 v131, 0x58, v243
	s_nop 0
	v_cndmask_b32_e32 v77, v184, v77, vcc
	v_cmp_le_i32_e32 vcc, v131, v125
	v_add_u32_e32 v131, 0x78, v243
	s_nop 0
	v_cndmask_b32_e32 v94, v184, v94, vcc
	v_cmp_le_i32_e32 vcc, v131, v125
	v_add_u32_e32 v131, 0x59, v243
	s_nop 0
	v_cndmask_b32_e32 v78, v184, v78, vcc
	v_cmp_le_i32_e32 vcc, v131, v125
	v_add_u32_e32 v131, 0x79, v243
	s_nop 0
	v_cndmask_b32_e32 v95, v184, v95, vcc
	v_cmp_le_i32_e32 vcc, v131, v125
	v_add_u32_e32 v131, 0x5a, v243
	s_nop 0
	v_cndmask_b32_e32 v79, v184, v79, vcc
	v_cmp_le_i32_e32 vcc, v131, v125
	v_add_u32_e32 v131, 0x7a, v243
	s_nop 0
	v_cndmask_b32_e32 v96, v184, v96, vcc
	v_cmp_le_i32_e32 vcc, v131, v125
	v_add_u32_e32 v131, 0x5b, v243
	v_add_u32_e32 v243, 0x7b, v243
	v_cndmask_b32_e32 v80, v184, v80, vcc
	v_cmp_le_i32_e32 vcc, v131, v125
	s_nop 1
	v_cndmask_b32_e32 v97, v184, v97, vcc
	v_cmp_le_i32_e32 vcc, v243, v125
	s_nop 1
	v_cndmask_b32_e32 v81, v184, v81, vcc
	v_max3_f32 v0, v82, v83, v84
	v_max3_f32 v0, v0, v85, v86
	v_max3_f32 v0, v0, v87, v88
	v_max3_f32 v0, v0, v89, v90
	v_max3_f32 v0, v0, v91, v92
	v_max3_f32 v0, v0, v93, v94
	v_max3_f32 v0, v0, v95, v96
	v_max_f32_e32 v0, v0, v97
	v_fmac_f32_e32 v0, v127, v250
	s_nop 1
	v_max3_f32 v120, v66, v67, v68
	v_max3_f32 v120, v120, v69, v70
	v_max3_f32 v120, v120, v71, v72
	v_max3_f32 v120, v120, v73, v74
	v_max3_f32 v120, v120, v75, v76
	v_max3_f32 v120, v120, v77, v78
	v_max3_f32 v120, v120, v79, v80
	v_max_f32_e32 v120, v120, v81
	v_add_f32_e32 v120, v251, v120
	v_max_f32_e32 v0, v0, v120
	v_mov_b32_e32 v120, v0
	s_nop 1
	v_permlane32_swap_b32_e32 v0, v120
	v_max_f32_e32 v0, v0, v120
	v_cmp_lt_f32_e32 vcc, v0, v143
	v_max_f32_e32 v133, v133, v0
	v_mov_b32_e32 v255, v0
	s_andn2_b64 s[2:3], exec, vcc
	s_cbranch_scc0 .La_endB0
; #define LAS __attribute__((address_space(3)))
; __device__ __forceinline__ unsigned cvtpk(float lo, float hi) { return pg8::cvt_pk_bf16(lo, hi); }
; __device__ __forceinline__ float ex2(float v) { return __builtin_amdgcn_exp2f(v); }
; #define MFMA32(a, b, c) __builtin_amdgcn_mfma_f32_32x32x16_bf16((a), (b), (c), 0, 0, 0)
; __device__ __forceinline__ void unit(LAS unsigned char* lds, bf16_t* P1, const bf16_t* vaT, int b, int h, int qblk, float lam, const float* subln_w, const float* khalf) {
;     ...
;         for (int r = 0; r < 16; r += 2) { f32x2 a = (f32x2){S0[r], S0[r + 1]} + c0, bq = (f32x2){S1[r], S1[r + 1]} + c1;
;             a.x = ex2(a.x); a.y = ex2(a.y); bq.x = ex2(bq.x); bq.y = ex2(bq.y); S0[r] = a.x; S0[r + 1] = a.y; S1[r] = bq.x; S1[r + 1] = bq.y; ps2 = ps2 + a; ps2 = ps2 + bq; }
;         l = l * alpha + (ps2.x + ps2.y);
;         if (__any(alpha != 1.f)) {
; #pragma unroll
;             for (int d = 0; d < 4; ++d) O[d] = O[d] * alpha;
;         }
;         u32x4 pk[2][2];
; #pragma unroll
;         for (int s = 0; s < 2; ++s) {
;             pk[0][s] = (u32x4){cvtpk(S0[8 * s + 0], S0[8 * s + 1]), cvtpk(S0[8 * s + 2], S0[8 * s + 3]), cvtpk(S0[8 * s + 4], S0[8 * s + 5]), cvtpk(S0[8 * s + 6], S0[8 * s + 7])};
;             pk[1][s] = (u32x4){cvtpk(S1[8 * s + 0], S1[8 * s + 1]), cvtpk(S1[8 * s + 2], S1[8 * s + 3]), cvtpk(S1[8 * s + 4], S1[8 * s + 5]), cvtpk(S1[8 * s + 6], S1[8 * s + 7])};
;         }
; #pragma unroll
;         for (int d = 0; d < 4; ++d)
; #pragma unroll
;             for (int t2 = 0; t2 < 2; ++t2)
; #pragma unroll
;                 for (int s = 0; s < 2; ++s) {
;                     const bf16x8 vf = *(const LAS bf16x8*)(kb + voff[2 * t2 + s] + d * 32 * 128);
;                     O[d] = MFMA32(vf, __builtin_bit_cast(bf16x8, pk[t2][s]), O[d]);
;                 }
	v_add_f32_e32 v82, v142, v82
	v_add_f32_e32 v83, v142, v83
	v_add_f32_e32 v84, v142, v84
	v_add_f32_e32 v85, v142, v85
	v_add_f32_e32 v86, v142, v86
	v_add_f32_e32 v87, v142, v87
	v_add_f32_e32 v88, v142, v88
	v_add_f32_e32 v89, v142, v89
	v_exp_f32_e32 v82, v82
	v_exp_f32_e32 v83, v83
	v_exp_f32_e32 v84, v84
	v_exp_f32_e32 v85, v85
	v_exp_f32_e32 v86, v86
	v_exp_f32_e32 v87, v87
	v_exp_f32_e32 v88, v88
	v_exp_f32_e32 v89, v89
	v_add_f32_e32 v252, v82, v84
	v_add_f32_e32 v253, v83, v85
	v_cvt_pk_bf16_f32 v82, v82, v83
	v_cvt_pk_bf16_f32 v83, v84, v85
	v_cvt_pk_bf16_f32 v84, v86, v87
	v_cvt_pk_bf16_f32 v85, v88, v89
	v_add_f32_e32 v252, v252, v86
	v_add_f32_e32 v253, v253, v87
	v_add_f32_e32 v252, v252, v88
	v_add_f32_e32 v253, v253, v89
	s_waitcnt lgkmcnt(4)
	v_mfma_f32_32x32x16_bf16 v[50:65], v[192:195], v[82:85], v[50:65]
	ds_read_b128 v[192:195], v246 offset:49152
	v_add_f32_e32 v90, v142, v90
	v_add_f32_e32 v91, v142, v91
	v_add_f32_e32 v92, v142, v92
	v_add_f32_e32 v93, v142, v93
	v_add_f32_e32 v94, v142, v94
	v_add_f32_e32 v95, v142, v95
	v_add_f32_e32 v96, v142, v96
	v_mfma_f32_32x32x16_bf16 v[34:49], v[202:205], v[82:85], v[34:49]
	ds_read_b128 v[202:205], v246 offset:53248
	v_add_f32_e32 v97, v142, v97
	v_exp_f32_e32 v90, v90
	v_exp_f32_e32 v91, v91
	v_exp_f32_e32 v92, v92
	v_exp_f32_e32 v93, v93
	v_exp_f32_e32 v94, v94
	v_exp_f32_e32 v95, v95
	v_mfma_f32_32x32x16_bf16 v[18:33], v[210:213], v[82:85], v[18:33]
	ds_read_b128 v[210:213], v246 offset:57344
	v_exp_f32_e32 v96, v96
	v_exp_f32_e32 v97, v97
	v_add_f32_e32 v252, v252, v90
	v_add_f32_e32 v253, v253, v91
	v_add_f32_e32 v252, v252, v92
	v_add_f32_e32 v253, v253, v93
	v_cvt_pk_bf16_f32 v90, v90, v91
	v_mfma_f32_32x32x16_bf16 v[2:17], v[218:221], v[82:85], v[2:17]
	ds_read_b128 v[218:221], v246 offset:61440
	v_cvt_pk_bf16_f32 v91, v92, v93
	v_cvt_pk_bf16_f32 v92, v94, v95
	v_cvt_pk_bf16_f32 v93, v96, v97
	v_add_f32_e32 v252, v252, v94
	v_add_f32_e32 v253, v253, v95
	v_add_f32_e32 v252, v252, v96
	v_add_f32_e32 v253, v253, v97
	s_waitcnt lgkmcnt(4)
	v_mfma_f32_32x32x16_bf16 v[50:65], v[196:199], v[90:93], v[50:65]
	ds_read_b128 v[196:199], v247 offset:49152
	v_add_f32_e32 v66, v248, v66
	v_add_f32_e32 v67, v248, v67
	v_add_f32_e32 v68, v248, v68
	v_add_f32_e32 v69, v248, v69
	v_add_f32_e32 v70, v248, v70
	v_add_f32_e32 v71, v248, v71
	v_add_f32_e32 v72, v248, v72
	v_mfma_f32_32x32x16_bf16 v[34:49], v[206:209], v[90:93], v[34:49]
	ds_read_b128 v[206:209], v247 offset:53248
	v_add_f32_e32 v73, v248, v73
	v_exp_f32_e32 v66, v66
	v_exp_f32_e32 v67, v67
	v_exp_f32_e32 v68, v68
	v_exp_f32_e32 v69, v69
	v_exp_f32_e32 v70, v70
	v_exp_f32_e32 v71, v71
	v_mfma_f32_32x32x16_bf16 v[18:33], v[214:217], v[90:93], v[18:33]
	ds_read_b128 v[214:217], v247 offset:57344
	v_exp_f32_e32 v72, v72
	v_exp_f32_e32 v73, v73
	v_add_f32_e32 v252, v252, v66
	v_add_f32_e32 v253, v253, v67
	v_add_f32_e32 v252, v252, v68
	v_add_f32_e32 v253, v253, v69
	v_cvt_pk_bf16_f32 v66, v66, v67
	v_mfma_f32_32x32x16_bf16 v[2:17], v[222:225], v[90:93], v[2:17]
	ds_read_b128 v[222:225], v247 offset:61440
	v_cvt_pk_bf16_f32 v67, v68, v69
	v_cvt_pk_bf16_f32 v68, v70, v71
	v_cvt_pk_bf16_f32 v69, v72, v73
	v_add_f32_e32 v252, v252, v70
	v_add_f32_e32 v253, v253, v71
	v_add_f32_e32 v252, v252, v72
	v_add_f32_e32 v253, v253, v73
	s_waitcnt lgkmcnt(4)
	v_mfma_f32_32x32x16_bf16 v[50:65], v[192:195], v[66:69], v[50:65]
	v_add_f32_e32 v74, v248, v74
	v_add_f32_e32 v75, v248, v75
	v_add_f32_e32 v76, v248, v76
	v_add_f32_e32 v77, v248, v77
	v_add_f32_e32 v78, v248, v78
	v_add_f32_e32 v79, v248, v79
	v_add_f32_e32 v80, v248, v80
	v_mfma_f32_32x32x16_bf16 v[34:49], v[202:205], v[66:69], v[34:49]
	v_add_f32_e32 v81, v248, v81
	v_exp_f32_e32 v74, v74
	v_exp_f32_e32 v75, v75
	v_exp_f32_e32 v76, v76
	v_exp_f32_e32 v77, v77
	v_exp_f32_e32 v78, v78
	v_exp_f32_e32 v79, v79
	v_mfma_f32_32x32x16_bf16 v[18:33], v[210:213], v[66:69], v[18:33]
	v_exp_f32_e32 v80, v80
	v_exp_f32_e32 v81, v81
	v_add_f32_e32 v252, v252, v74
	v_add_f32_e32 v253, v253, v75
	v_add_f32_e32 v252, v252, v76
	v_add_f32_e32 v253, v253, v77
	v_cvt_pk_bf16_f32 v74, v74, v75
	v_mfma_f32_32x32x16_bf16 v[2:17], v[218:221], v[66:69], v[2:17]
	v_cvt_pk_bf16_f32 v75, v76, v77
	v_cvt_pk_bf16_f32 v76, v78, v79
	v_cvt_pk_bf16_f32 v77, v80, v81
	v_add_f32_e32 v252, v252, v78
	v_add_f32_e32 v253, v253, v79
	v_add_f32_e32 v252, v252, v80
	v_add_f32_e32 v253, v253, v81
	s_waitcnt lgkmcnt(0)
	v_mfma_f32_32x32x16_bf16 v[50:65], v[196:199], v[74:77], v[50:65]
	v_add_f32_e32 v250, v252, v253
	v_mfma_f32_32x32x16_bf16 v[34:49], v[206:209], v[74:77], v[34:49]
	v_add_f32_e32 v191, v191, v250
	v_mfma_f32_32x32x16_bf16 v[18:33], v[214:217], v[74:77], v[18:33]
	v_mfma_f32_32x32x16_bf16 v[2:17], v[222:225], v[74:77], v[2:17]

; __device__ __forceinline__ void unit(LAS unsigned char* lds, bf16_t* P1, const bf16_t* vaT, int b, int h, int qblk, float lam, const float* subln_w, const float* khalf) {
;     ...
;         { const bool done = __all(qbound + sl2 * (float)(64 * j + 63 - qrow) < m - 24.f);
;           if (lane == 0) dflag[(jj & 1) * 8 + wid] = done ? 1 : 0; }
;         if (jj + 2 < NT) asm volatile("s_waitcnt vmcnt(8) lgkmcnt(0)\n\ts_barrier" ::: "memory"); else if (jj + 1 < NT) asm volatile("s_waitcnt vmcnt(4) lgkmcnt(0)\n\ts_barrier" ::: "memory"); else asm volatile("s_waitcnt vmcnt(0) lgkmcnt(0)\n\ts_barrier" ::: "memory");
;         { typedef int i32x4 __attribute__((ext_vector_type(4)));
;           const i32x4 fa = *(const LAS i32x4*)(lds + 4 * STG + (jj & 1) * 32), fb = *(const LAS i32x4*)(lds + 4 * STG + (jj & 1) * 32 + 16);
;           if (((fa[0] + fa[1]) + (fa[2] + fa[3])) + ((fb[0] + fb[1]) + (fb[2] + fb[3])) == 8) break; }
;         if (jj + 3 < NT) { DMA_TILE(j - 3, (stg + 3) & 3); }
;         const LAS unsigned char* kb = lds + stg * STG;
;         stg = (stg + 1) & 3;
;         f32x16 S0, S1;
;         { float slv = sl2; asm volatile("" : "+v"(slv));
; #pragma unroll
;           for (int r = 0; r < 16; ++r) { S0[r] = __builtin_fmaf(slv, (float)((r & 3) + 8 * (r >> 2)), sl2h); S1[r] = S0[r]; } }
; #pragma unroll
;         for (int ks = 0; ks < 4; ++ks) {
;             const bf16x8 a0 = *(const LAS bf16x8*)(kb + koff[ks]);
;             const bf16x8 a1 = *(const LAS bf16x8*)(kb + koff[ks] + 32 * 256);
;             S0 = MFMA32(a0, qf[ks], S0); S1 = MFMA32(a1, qf[ks], S1);
;         }
;         const int kv0 = 64 * j;
;         if (j >= NT - 2) {
; #pragma unroll
;             for (int r = 0; r < 16; ++r) { const int kv = kv0 + crow(r, hi); if (kv > qrow) S0[r] = -INFINITY; if (kv + 32 > qrow) S1[r] = -INFINITY; }
;         }
;         const float tb0 = sl2 * (float)(kv0 - qrow), tb1 = tb0 + sl2 * 32.f;
;         float mx0 = S0[0], mx1 = S1[0];
; #pragma unroll
;         for (int r = 1; r < 16; ++r) { mx0 = fmaxf(mx0, S0[r]); mx1 = fmaxf(mx1, S1[r]); }
;         float mt = fmaxf(mx0 + tb0, mx1 + tb1); mt = fmaxf(mt, __shfl_xor(mt, 32));
;         const bool skip = __all((mt < m - 24.f) || (mt == -INFINITY));
;         if (!skip) {
;         const float mn = fmaxf(m, mt); const float alpha = ex2(m - mn); m = mn;
;         const float c0 = tb0 - mn, c1 = tb1 - mn;
.La_after_bar:
	s_lshl_b32 s82, s80, 15
	s_add_i32 s83, s82, 0x8000
	s_sub_i32 s100, s76, 64
	s_and_b32 s2, s81, 2
	s_lshl_b32 s2, s2, 4
	s_add_i32 s2, s2, 0x20000
	v_mov_b32_e32 v70, s2
	ds_read_b128 v[66:69], v70
	ds_read_b128 v[70:73], v70 offset:16
	v_add3_u32 v201, s82, v129, v151
	v_add3_u32 v135, s82, v185, v151
	v_add3_u32 v249, s82, v186, v151
	v_add3_u32 v254, s82, v187, v151
	ds_read_b128 v[192:195], v201
	ds_read_b128 v[202:205], v135
	ds_read_b128 v[210:213], v249
	ds_read_b128 v[218:221], v254
	ds_read_b128 v[196:199], v201 offset:8192
	ds_read_b128 v[206:209], v135 offset:8192
	ds_read_b128 v[214:217], v249 offset:8192
	ds_read_b128 v[222:225], v254 offset:8192
	s_waitcnt lgkmcnt(8)
	v_add3_u32 v66, v66, v67, v68
	v_add3_u32 v69, v69, v70, v71
	v_add_u32_e32 v72, v72, v73
	v_add3_u32 v66, v66, v69, v72
	v_cmp_eq_u32_e32 vcc, 8, v66
	s_cbranch_vccnz .LBB0_420
	s_add_i32 s5, s81, 2
	s_cmp_ge_u32 s5, s73
	s_cbranch_scc1 .La_qk_nodmaA
	s_add_i32 s5, s82, 0x10000
	s_and_b32 s5, s5, 0x18000
	s_add_i32 s5, s72, s5
	s_mov_b32 m0, s5
	s_waitcnt lgkmcnt(4)
	v_mfma_f32_32x32x16_bf16 v[82:97], v[192:195], v[98:101], v[226:241]
	global_load_lds_dwordx4 v[140:141], off
	s_add_i32 m0, s5, 0x400
	v_add_u32_e32 v244, s82, v168
	v_add_u32_e32 v245, s82, v169
	v_add_u32_e32 v246, s82, v170
	v_mfma_f32_32x32x16_bf16 v[82:97], v[202:205], v[102:105], v[82:97]
	global_load_lds_dwordx4 v[138:139], off
	s_add_i32 m0, s5, 0x4000
	v_add_u32_e32 v247, s82, v171
	v_add_f32_e32 v143, v133, v121
	v_fma_f32 v251, v127, v137, v188
	v_mfma_f32_32x32x16_bf16 v[82:97], v[210:213], v[106:109], v[82:97]
	global_load_lds_dwordx4 v134, s[44:45]
	s_add_i32 m0, s5, 0x4400
	v_fma_f32 v142, v127, v137, -v132
	v_max_f32_e32 v143, 0xff7fffff, v143
	v_add_f32_e32 v248, v142, v188
	v_mfma_f32_32x32x16_bf16 v[82:97], v[218:221], v[110:113], v[82:97]
	global_load_lds_dwordx4 v136, s[44:45]
	v_fma_f32 v255, v188, -2.0, v255
	v_add_f32_e32 v243, 4.0, v143
	ds_read_b128 v[192:195], v244 offset:16384
	ds_read_b128 v[202:205], v244 offset:20480
	ds_read_b128 v[210:213], v244 offset:24576
	ds_read_b128 v[218:221], v244 offset:28672
	s_waitcnt lgkmcnt(4)
	v_mfma_f32_32x32x16_bf16 v[66:81], v[196:199], v[98:101], v[226:241]
	s_add_u32 s44, s44, 0xffffff80
	s_addc_u32 s45, s45, -1
	v_lshl_add_u64 v[138:139], v[138:139], 0, s[38:39]
	v_lshl_add_u64 v[140:141], v[140:141], 0, s[38:39]
	v_mfma_f32_32x32x16_bf16 v[66:81], v[206:209], v[102:105], v[66:81]
	v_max3_f32 v0, v82, v83, v84
	v_max3_f32 v0, v0, v85, v86
	v_max3_f32 v0, v0, v87, v88
	v_max3_f32 v0, v0, v89, v90
	v_add_f32_e32 v82, v142, v82
	v_add_f32_e32 v83, v142, v83
	v_add_f32_e32 v84, v142, v84
	v_add_f32_e32 v85, v142, v85
	v_mfma_f32_32x32x16_bf16 v[66:81], v[214:217], v[106:109], v[66:81]
	v_add_f32_e32 v86, v142, v86
	v_add_f32_e32 v87, v142, v87
	v_add_f32_e32 v88, v142, v88
	v_add_f32_e32 v89, v142, v89
	v_exp_f32_e32 v82, v82
	v_exp_f32_e32 v83, v83
	v_exp_f32_e32 v84, v84
	v_max3_f32 v0, v0, v91, v92
	v_mfma_f32_32x32x16_bf16 v[66:81], v[222:225], v[110:113], v[66:81]
	v_exp_f32_e32 v85, v85
	v_exp_f32_e32 v86, v86
	v_exp_f32_e32 v87, v87
	v_max3_f32 v0, v0, v93, v94
	v_exp_f32_e32 v88, v88
	v_exp_f32_e32 v89, v89
	v_max3_f32 v0, v0, v95, v96
	v_max_f32_e32 v0, v0, v97
	v_cmp_ge_f32_e32 vcc, v255, v243

; #define LAS __attribute__((address_space(3)))
; __device__ __forceinline__ unsigned cvtpk(float lo, float hi) { return pg8::cvt_pk_bf16(lo, hi); }
; __device__ __forceinline__ void unit(LAS unsigned char* lds, bf16_t* P1, const bf16_t* vaT, int b, int h, int qblk, float lam, const float* subln_w, const float* khalf) {
;     ...
;         if (jj + 3 < NT) { DMA_TILE(j - 3, (stg + 3) & 3); }
;         const LAS unsigned char* kb = lds + stg * STG;
;         stg = (stg + 1) & 3;
;         f32x16 S0, S1;
;         { float slv = sl2; asm volatile("" : "+v"(slv));
; #pragma unroll
;           for (int r = 0; r < 16; ++r) { S0[r] = __builtin_fmaf(slv, (float)((r & 3) + 8 * (r >> 2)), sl2h); S1[r] = S0[r]; } }
; #pragma unroll
;         for (int ks = 0; ks < 4; ++ks) {
;             const bf16x8 a0 = *(const LAS bf16x8*)(kb + koff[ks]);
;             const bf16x8 a1 = *(const LAS bf16x8*)(kb + koff[ks] + 32 * 256);
;             S0 = MFMA32(a0, qf[ks], S0); S1 = MFMA32(a1, qf[ks], S1);
;         }
;         const int kv0 = 64 * j;
;         if (j >= NT - 2) {
; #pragma unroll
;     ...
;         for (int r = 0; r < 16; r += 2) { f32x2 a = (f32x2){S0[r], S0[r + 1]} + c0, bq = (f32x2){S1[r], S1[r + 1]} + c1;
;             a.x = ex2(a.x); a.y = ex2(a.y); bq.x = ex2(bq.x); bq.y = ex2(bq.y); S0[r] = a.x; S0[r + 1] = a.y; S1[r] = bq.x; S1[r + 1] = bq.y; ps2 = ps2 + a; ps2 = ps2 + bq; }
;         l = l * alpha + (ps2.x + ps2.y);
;         if (__any(alpha != 1.f)) {
; #pragma unroll
;             for (int d = 0; d < 4; ++d) O[d] = O[d] * alpha;
;         }
;         u32x4 pk[2][2];
; #pragma unroll
;         for (int s = 0; s < 2; ++s) {
;             pk[0][s] = (u32x4){cvtpk(S0[8 * s + 0], S0[8 * s + 1]), cvtpk(S0[8 * s + 2], S0[8 * s + 3]), cvtpk(S0[8 * s + 4], S0[8 * s + 5]), cvtpk(S0[8 * s + 6], S0[8 * s + 7])};
;             pk[1][s] = (u32x4){cvtpk(S1[8 * s + 0], S1[8 * s + 1]), cvtpk(S1[8 * s + 2], S1[8 * s + 3]), cvtpk(S1[8 * s + 4], S1[8 * s + 5]), cvtpk(S1[8 * s + 6], S1[8 * s + 7])};
;         }
; #pragma unroll
;         for (int d = 0; d < 4; ++d)
; #pragma unroll
;             for (int t2 = 0; t2 < 2; ++t2)
; #pragma unroll
;                 for (int s = 0; s < 2; ++s) {
;                     const bf16x8 vf = *(const LAS bf16x8*)(kb + voff[2 * t2 + s] + d * 32 * 128);
;                     O[d] = MFMA32(vf, __builtin_bit_cast(bf16x8, pk[t2][s]), O[d]);
;                 }
.La_nomaxA:
	v_add_f32_e32 v252, v82, v84
	v_add_f32_e32 v253, v83, v85
	v_cvt_pk_bf16_f32 v82, v82, v83
	v_cvt_pk_bf16_f32 v83, v84, v85
	v_cvt_pk_bf16_f32 v84, v86, v87
	v_cvt_pk_bf16_f32 v85, v88, v89
	v_add_f32_e32 v252, v252, v86
	v_add_f32_e32 v253, v253, v87
	v_add_f32_e32 v252, v252, v88
	v_add_f32_e32 v253, v253, v89
	s_waitcnt lgkmcnt(4)
	v_mfma_f32_32x32x16_bf16 v[50:65], v[192:195], v[82:85], v[50:65]
	ds_read_b128 v[192:195], v246 offset:16384
	v_add_f32_e32 v90, v142, v90
	v_add_f32_e32 v91, v142, v91
	v_add_f32_e32 v92, v142, v92
	v_add_f32_e32 v93, v142, v93
	v_add_f32_e32 v94, v142, v94
	v_add_f32_e32 v95, v142, v95
	v_add_f32_e32 v96, v142, v96
	v_mfma_f32_32x32x16_bf16 v[34:49], v[202:205], v[82:85], v[34:49]
	ds_read_b128 v[202:205], v246 offset:20480
	v_add_f32_e32 v97, v142, v97
	v_exp_f32_e32 v90, v90
	v_exp_f32_e32 v91, v91
	v_exp_f32_e32 v92, v92
	v_exp_f32_e32 v93, v93
	v_exp_f32_e32 v94, v94
	v_exp_f32_e32 v95, v95
	v_mfma_f32_32x32x16_bf16 v[18:33], v[210:213], v[82:85], v[18:33]
	ds_read_b128 v[210:213], v246 offset:24576
	v_exp_f32_e32 v96, v96
	v_exp_f32_e32 v97, v97
	v_add_f32_e32 v252, v252, v90
	v_add_f32_e32 v253, v253, v91
	v_add_f32_e32 v252, v252, v92
	v_add_f32_e32 v253, v253, v93
	v_cvt_pk_bf16_f32 v90, v90, v91
	v_mfma_f32_32x32x16_bf16 v[2:17], v[218:221], v[82:85], v[2:17]
	ds_read_b128 v[218:221], v246 offset:28672
	v_cvt_pk_bf16_f32 v91, v92, v93
	v_cvt_pk_bf16_f32 v92, v94, v95
	v_cvt_pk_bf16_f32 v93, v96, v97
	v_add_f32_e32 v252, v252, v94
	v_add_f32_e32 v253, v253, v95
	v_add_f32_e32 v252, v252, v96
	v_add_f32_e32 v253, v253, v97
	s_waitcnt lgkmcnt(4)
	v_mfma_f32_32x32x16_bf16 v[50:65], v[196:199], v[90:93], v[50:65]
	ds_read_b128 v[196:199], v247 offset:16384
	v_add_f32_e32 v66, v248, v66
	v_add_f32_e32 v67, v248, v67
	v_add_f32_e32 v68, v248, v68
	v_add_f32_e32 v69, v248, v69
	v_add_f32_e32 v70, v248, v70
	v_add_f32_e32 v71, v248, v71
	v_add_f32_e32 v72, v248, v72
	v_mfma_f32_32x32x16_bf16 v[34:49], v[206:209], v[90:93], v[34:49]
	ds_read_b128 v[206:209], v247 offset:20480
	v_add_f32_e32 v73, v248, v73
	v_exp_f32_e32 v66, v66
	v_exp_f32_e32 v67, v67
	v_exp_f32_e32 v68, v68
	v_exp_f32_e32 v69, v69
	v_exp_f32_e32 v70, v70
	v_exp_f32_e32 v71, v71
	v_mfma_f32_32x32x16_bf16 v[18:33], v[214:217], v[90:93], v[18:33]
	ds_read_b128 v[214:217], v247 offset:24576
	v_exp_f32_e32 v72, v72
	v_exp_f32_e32 v73, v73
	v_add_f32_e32 v252, v252, v66
	v_add_f32_e32 v253, v253, v67
	v_add_f32_e32 v252, v252, v68
	v_add_f32_e32 v253, v253, v69
	v_cvt_pk_bf16_f32 v66, v66, v67
	v_mfma_f32_32x32x16_bf16 v[2:17], v[222:225], v[90:93], v[2:17]
	ds_read_b128 v[222:225], v247 offset:28672
	v_cvt_pk_bf16_f32 v67, v68, v69
	v_cvt_pk_bf16_f32 v68, v70, v71
	v_cvt_pk_bf16_f32 v69, v72, v73
	v_add_f32_e32 v252, v252, v70
	v_add_f32_e32 v253, v253, v71
	v_add_f32_e32 v252, v252, v72
	v_add_f32_e32 v253, v253, v73
	s_waitcnt lgkmcnt(4)
	v_mfma_f32_32x32x16_bf16 v[50:65], v[192:195], v[66:69], v[50:65]
	v_add_f32_e32 v74, v248, v74
	v_add_f32_e32 v75, v248, v75
	v_add_f32_e32 v76, v248, v76
	v_add_f32_e32 v77, v248, v77
	v_add_f32_e32 v78, v248, v78
	v_add_f32_e32 v79, v248, v79
	v_add_f32_e32 v80, v248, v80
	v_mfma_f32_32x32x16_bf16 v[34:49], v[202:205], v[66:69], v[34:49]
	v_add_f32_e32 v81, v248, v81
	v_exp_f32_e32 v74, v74
	v_exp_f32_e32 v75, v75
	v_exp_f32_e32 v76, v76
	v_exp_f32_e32 v77, v77
	v_exp_f32_e32 v78, v78
	v_exp_f32_e32 v79, v79
	v_mfma_f32_32x32x16_bf16 v[18:33], v[210:213], v[66:69], v[18:33]
	v_exp_f32_e32 v80, v80
	v_exp_f32_e32 v81, v81
	v_add_f32_e32 v252, v252, v74
	v_add_f32_e32 v253, v253, v75
	v_add_f32_e32 v252, v252, v76
	v_add_f32_e32 v253, v253, v77
	v_cvt_pk_bf16_f32 v74, v74, v75
	v_mfma_f32_32x32x16_bf16 v[2:17], v[218:221], v[66:69], v[2:17]
	v_cvt_pk_bf16_f32 v75, v76, v77
	v_cvt_pk_bf16_f32 v76, v78, v79
	v_cvt_pk_bf16_f32 v77, v80, v81
	v_add_f32_e32 v252, v252, v78
	v_add_f32_e32 v253, v253, v79
	v_add_f32_e32 v252, v252, v80
	v_add_f32_e32 v253, v253, v81
	s_waitcnt lgkmcnt(0)
	v_mfma_f32_32x32x16_bf16 v[50:65], v[196:199], v[74:77], v[50:65]
	v_add_f32_e32 v250, v252, v253
	v_mfma_f32_32x32x16_bf16 v[34:49], v[206:209], v[74:77], v[34:49]
	v_add_f32_e32 v191, v191, v250
	v_mfma_f32_32x32x16_bf16 v[18:33], v[214:217], v[74:77], v[18:33]
	v_mfma_f32_32x32x16_bf16 v[2:17], v[222:225], v[74:77], v[2:17]
.La_endA:
	ds_read_b128 v[192:195], v201 offset:32768
	ds_read_b128 v[202:205], v135 offset:32768
	ds_read_b128 v[210:213], v249 offset:32768
	ds_read_b128 v[218:221], v254 offset:32768
	ds_read_b128 v[196:199], v201 offset:40960
	ds_read_b128 v[206:209], v135 offset:40960
	ds_read_b128 v[214:217], v249 offset:40960
	ds_read_b128 v[222:225], v254 offset:40960
	s_add_i32 s5, s81, 3
	s_cmp_ge_u32 s5, s73
	s_cbranch_scc1 .La_qk_nodmaB
	s_add_i32 s5, s82, 0x18000
	s_and_b32 s5, s5, 0x18000
	s_add_i32 s5, s72, s5
	s_mov_b32 m0, s5
	s_waitcnt lgkmcnt(4)
	v_mfma_f32_32x32x16_bf16 v[82:97], v[192:195], v[98:101], v[226:241]
	global_load_lds_dwordx4 v[140:141], off
	s_add_i32 m0, s5, 0x400
	v_add_f32_e32 v250, 0xc2800000, v137
	v_add_f32_e32 v143, v133, v121
	v_mfma_f32_32x32x16_bf16 v[82:97], v[202:205], v[102:105], v[82:97]
	global_load_lds_dwordx4 v[138:139], off
	s_add_i32 m0, s5, 0x4000
	v_fma_f32 v251, v127, v250, v188
	v_fma_f32 v142, v127, v250, -v132
	v_mfma_f32_32x32x16_bf16 v[82:97], v[210:213], v[106:109], v[82:97]
	global_load_lds_dwordx4 v134, s[44:45]
	s_add_i32 m0, s5, 0x4400
	v_max_f32_e32 v143, 0xff7fffff, v143
	v_add_f32_e32 v248, v142, v188
	v_mfma_f32_32x32x16_bf16 v[82:97], v[218:221], v[110:113], v[82:97]
	global_load_lds_dwordx4 v136, s[44:45]
	v_fma_f32 v255, v188, -2.0, v255
	v_add_f32_e32 v243, 4.0, v143
	ds_read_b128 v[192:195], v244 offset:49152
	ds_read_b128 v[202:205], v244 offset:53248
	ds_read_b128 v[210:213], v244 offset:57344
	ds_read_b128 v[218:221], v244 offset:61440
	s_waitcnt lgkmcnt(4)
	v_mfma_f32_32x32x16_bf16 v[66:81], v[196:199], v[98:101], v[226:241]
	s_add_u32 s44, s44, 0xffffff80
	s_addc_u32 s45, s45, -1
	v_lshl_add_u64 v[138:139], v[138:139], 0, s[38:39]
	v_lshl_add_u64 v[140:141], v[140:141], 0, s[38:39]
	v_mfma_f32_32x32x16_bf16 v[66:81], v[206:209], v[102:105], v[66:81]
	v_max3_f32 v0, v82, v83, v84
	v_max3_f32 v0, v0, v85, v86
	v_max3_f32 v0, v0, v87, v88
	v_max3_f32 v0, v0, v89, v90
	v_add_f32_e32 v82, v142, v82
	v_add_f32_e32 v83, v142, v83
	v_add_f32_e32 v84, v142, v84
	v_add_f32_e32 v85, v142, v85
	v_mfma_f32_32x32x16_bf16 v[66:81], v[214:217], v[106:109], v[66:81]
	v_add_f32_e32 v86, v142, v86
	v_add_f32_e32 v87, v142, v87
	v_add_f32_e32 v88, v142, v88
	v_add_f32_e32 v89, v142, v89
	v_exp_f32_e32 v82, v82
	v_exp_f32_e32 v83, v83
	v_exp_f32_e32 v84, v84
	v_max3_f32 v0, v0, v91, v92
	v_mfma_f32_32x32x16_bf16 v[66:81], v[222:225], v[110:113], v[66:81]
	v_exp_f32_e32 v85, v85
	v_exp_f32_e32 v86, v86
	v_exp_f32_e32 v87, v87
	v_max3_f32 v0, v0, v93, v94
	v_exp_f32_e32 v88, v88
	v_exp_f32_e32 v89, v89
	v_max3_f32 v0, v0, v95, v96
	v_max_f32_e32 v0, v0, v97
	v_cmp_ge_f32_e32 vcc, v255, v243

; #define LAS __attribute__((address_space(3)))
; __device__ __forceinline__ unsigned cvtpk(float lo, float hi) { return pg8::cvt_pk_bf16(lo, hi); }
; __device__ __forceinline__ float ex2(float v) { return __builtin_amdgcn_exp2f(v); }
; #define MFMA32(a, b, c) __builtin_amdgcn_mfma_f32_32x32x16_bf16((a), (b), (c), 0, 0, 0)
; __device__ __forceinline__ void unit(LAS unsigned char* lds, bf16_t* P1, const bf16_t* vaT, int b, int h, int qblk, float lam, const float* subln_w, const float* khalf) {
;     ...
;         for (int r = 0; r < 16; r += 2) { f32x2 a = (f32x2){S0[r], S0[r + 1]} + c0, bq = (f32x2){S1[r], S1[r + 1]} + c1;
;             a.x = ex2(a.x); a.y = ex2(a.y); bq.x = ex2(bq.x); bq.y = ex2(bq.y); S0[r] = a.x; S0[r + 1] = a.y; S1[r] = bq.x; S1[r + 1] = bq.y; ps2 = ps2 + a; ps2 = ps2 + bq; }
;         l = l * alpha + (ps2.x + ps2.y);
;         if (__any(alpha != 1.f)) {
; #pragma unroll
;             for (int d = 0; d < 4; ++d) O[d] = O[d] * alpha;
;         }
;         u32x4 pk[2][2];
; #pragma unroll
;         for (int s = 0; s < 2; ++s) {
;             pk[0][s] = (u32x4){cvtpk(S0[8 * s + 0], S0[8 * s + 1]), cvtpk(S0[8 * s + 2], S0[8 * s + 3]), cvtpk(S0[8 * s + 4], S0[8 * s + 5]), cvtpk(S0[8 * s + 6], S0[8 * s + 7])};
;             pk[1][s] = (u32x4){cvtpk(S1[8 * s + 0], S1[8 * s + 1]), cvtpk(S1[8 * s + 2], S1[8 * s + 3]), cvtpk(S1[8 * s + 4], S1[8 * s + 5]), cvtpk(S1[8 * s + 6], S1[8 * s + 7])};
;         }
; #pragma unroll
;         for (int d = 0; d < 4; ++d)
; #pragma unroll
;             for (int t2 = 0; t2 < 2; ++t2)
; #pragma unroll
;                 for (int s = 0; s < 2; ++s) {
;                     const bf16x8 vf = *(const LAS bf16x8*)(kb + voff[2 * t2 + s] + d * 32 * 128);
;                     O[d] = MFMA32(vf, __builtin_bit_cast(bf16x8, pk[t2][s]), O[d]);
;                 }
.La_nomaxB:
	v_add_f32_e32 v252, v82, v84
	v_add_f32_e32 v253, v83, v85
	v_cvt_pk_bf16_f32 v82, v82, v83
	v_cvt_pk_bf16_f32 v83, v84, v85
	v_cvt_pk_bf16_f32 v84, v86, v87
	v_cvt_pk_bf16_f32 v85, v88, v89
	v_add_f32_e32 v252, v252, v86
	v_add_f32_e32 v253, v253, v87
	v_add_f32_e32 v252, v252, v88
	v_add_f32_e32 v253, v253, v89
	s_waitcnt lgkmcnt(4)
	v_mfma_f32_32x32x16_bf16 v[50:65], v[192:195], v[82:85], v[50:65]
	ds_read_b128 v[192:195], v246 offset:49152
	v_add_f32_e32 v90, v142, v90
	v_add_f32_e32 v91, v142, v91
	v_add_f32_e32 v92, v142, v92
	v_add_f32_e32 v93, v142, v93
	v_add_f32_e32 v94, v142, v94
	v_add_f32_e32 v95, v142, v95
	v_add_f32_e32 v96, v142, v96
	v_mfma_f32_32x32x16_bf16 v[34:49], v[202:205], v[82:85], v[34:49]
	ds_read_b128 v[202:205], v246 offset:53248
	v_add_f32_e32 v97, v142, v97
	v_exp_f32_e32 v90, v90
	v_exp_f32_e32 v91, v91
	v_exp_f32_e32 v92, v92
	v_exp_f32_e32 v93, v93
	v_exp_f32_e32 v94, v94
	v_exp_f32_e32 v95, v95
	v_mfma_f32_32x32x16_bf16 v[18:33], v[210:213], v[82:85], v[18:33]
	ds_read_b128 v[210:213], v246 offset:57344
	v_exp_f32_e32 v96, v96
	v_exp_f32_e32 v97, v97
	v_add_f32_e32 v252, v252, v90
	v_add_f32_e32 v253, v253, v91
	v_add_f32_e32 v252, v252, v92
	v_add_f32_e32 v253, v253, v93
	v_cvt_pk_bf16_f32 v90, v90, v91
	v_mfma_f32_32x32x16_bf16 v[2:17], v[218:221], v[82:85], v[2:17]
	ds_read_b128 v[218:221], v246 offset:61440
	v_cvt_pk_bf16_f32 v91, v92, v93
	v_cvt_pk_bf16_f32 v92, v94, v95
	v_cvt_pk_bf16_f32 v93, v96, v97
	v_add_f32_e32 v252, v252, v94
	v_add_f32_e32 v253, v253, v95
	v_add_f32_e32 v252, v252, v96
	v_add_f32_e32 v253, v253, v97
	s_waitcnt lgkmcnt(4)
	v_mfma_f32_32x32x16_bf16 v[50:65], v[196:199], v[90:93], v[50:65]
	ds_read_b128 v[196:199], v247 offset:49152
	v_add_f32_e32 v66, v248, v66
	v_add_f32_e32 v67, v248, v67
	v_add_f32_e32 v68, v248, v68
	v_add_f32_e32 v69, v248, v69
	v_add_f32_e32 v70, v248, v70
	v_add_f32_e32 v71, v248, v71
	v_add_f32_e32 v72, v248, v72
	v_mfma_f32_32x32x16_bf16 v[34:49], v[206:209], v[90:93], v[34:49]
	ds_read_b128 v[206:209], v247 offset:53248
	v_add_f32_e32 v73, v248, v73
	v_exp_f32_e32 v66, v66
	v_exp_f32_e32 v67, v67
	v_exp_f32_e32 v68, v68
	v_exp_f32_e32 v69, v69
	v_exp_f32_e32 v70, v70
	v_exp_f32_e32 v71, v71
	v_mfma_f32_32x32x16_bf16 v[18:33], v[214:217], v[90:93], v[18:33]
	ds_read_b128 v[214:217], v247 offset:57344
	v_exp_f32_e32 v72, v72
	v_exp_f32_e32 v73, v73
	v_add_f32_e32 v252, v252, v66
	v_add_f32_e32 v253, v253, v67
	v_add_f32_e32 v252, v252, v68
	v_add_f32_e32 v253, v253, v69
	v_cvt_pk_bf16_f32 v66, v66, v67
	v_mfma_f32_32x32x16_bf16 v[2:17], v[222:225], v[90:93], v[2:17]
	ds_read_b128 v[222:225], v247 offset:61440
	v_cvt_pk_bf16_f32 v67, v68, v69
	v_cvt_pk_bf16_f32 v68, v70, v71
	v_cvt_pk_bf16_f32 v69, v72, v73
	v_add_f32_e32 v252, v252, v70
	v_add_f32_e32 v253, v253, v71
	v_add_f32_e32 v252, v252, v72
	v_add_f32_e32 v253, v253, v73
	s_waitcnt lgkmcnt(4)
	v_mfma_f32_32x32x16_bf16 v[50:65], v[192:195], v[66:69], v[50:65]
	v_add_f32_e32 v74, v248, v74
	v_add_f32_e32 v75, v248, v75
	v_add_f32_e32 v76, v248, v76
	v_add_f32_e32 v77, v248, v77
	v_add_f32_e32 v78, v248, v78
	v_add_f32_e32 v79, v248, v79
	v_add_f32_e32 v80, v248, v80
	v_mfma_f32_32x32x16_bf16 v[34:49], v[202:205], v[66:69], v[34:49]
	v_add_f32_e32 v81, v248, v81
	v_exp_f32_e32 v74, v74
	v_exp_f32_e32 v75, v75
	v_exp_f32_e32 v76, v76
	v_exp_f32_e32 v77, v77
	v_exp_f32_e32 v78, v78
	v_exp_f32_e32 v79, v79
	v_mfma_f32_32x32x16_bf16 v[18:33], v[210:213], v[66:69], v[18:33]
	v_exp_f32_e32 v80, v80
	v_exp_f32_e32 v81, v81
	v_add_f32_e32 v252, v252, v74
	v_add_f32_e32 v253, v253, v75
	v_add_f32_e32 v252, v252, v76
	v_add_f32_e32 v253, v253, v77
	v_cvt_pk_bf16_f32 v74, v74, v75
	v_mfma_f32_32x32x16_bf16 v[2:17], v[218:221], v[66:69], v[2:17]
	v_cvt_pk_bf16_f32 v75, v76, v77
	v_cvt_pk_bf16_f32 v76, v78, v79
	v_cvt_pk_bf16_f32 v77, v80, v81
	v_add_f32_e32 v252, v252, v78
	v_add_f32_e32 v253, v253, v79
	v_add_f32_e32 v252, v252, v80
	v_add_f32_e32 v253, v253, v81
	s_waitcnt lgkmcnt(0)
	v_mfma_f32_32x32x16_bf16 v[50:65], v[196:199], v[74:77], v[50:65]
	v_add_f32_e32 v250, v252, v253
	v_mfma_f32_32x32x16_bf16 v[34:49], v[206:209], v[74:77], v[34:49]
	v_add_f32_e32 v191, v191, v250
	v_mfma_f32_32x32x16_bf16 v[18:33], v[214:217], v[74:77], v[18:33]
	v_mfma_f32_32x32x16_bf16 v[2:17], v[222:225], v[74:77], v[2:17]

; #define LAS __attribute__((address_space(3)))
; __device__ __forceinline__ int crow(int r, int hi) { return (r & 3) + 8 * (r >> 2) + 4 * hi; }
; __device__ __forceinline__ float ex2(float v) { return __builtin_amdgcn_exp2f(v); }
; #define MFMA32(a, b, c) __builtin_amdgcn_mfma_f32_32x32x16_bf16((a), (b), (c), 0, 0, 0)
; __device__ __forceinline__ void unit(LAS unsigned char* lds, bf16_t* P1, const bf16_t* vaT, int b, int h, int qblk, float lam, const float* subln_w, const float* khalf) {
;     ...
;         for (int ks = 0; ks < 4; ++ks) {
;             const bf16x8 a0 = *(const LAS bf16x8*)(kb + koff[ks]);
;             const bf16x8 a1 = *(const LAS bf16x8*)(kb + koff[ks] + 32 * 256);
;             S0 = MFMA32(a0, qf[ks], S0); S1 = MFMA32(a1, qf[ks], S1);
;         }
;         const int kv0 = 64 * j;
;         if (j >= NT - 2) {
; #pragma unroll
;             for (int r = 0; r < 16; ++r) { const int kv = kv0 + crow(r, hi); if (kv > qrow) S0[r] = -INFINITY; if (kv + 32 > qrow) S1[r] = -INFINITY; }
;         }
;         const float tb0 = sl2 * (float)(kv0 - qrow), tb1 = tb0 + sl2 * 32.f;
;         float mx0 = S0[0], mx1 = S1[0];
; #pragma unroll
;         for (int r = 1; r < 16; ++r) { mx0 = fmaxf(mx0, S0[r]); mx1 = fmaxf(mx1, S1[r]); }
;         float mt = fmaxf(mx0 + tb0, mx1 + tb1); mt = fmaxf(mt, __shfl_xor(mt, 32));
;         const bool skip = __all((mt < m - 24.f) || (mt == -INFINITY));
;         if (!skip) {
;         const float mn = fmaxf(m, mt); const float alpha = ex2(m - mn); m = mn;
;         const float c0 = tb0 - mn, c1 = tb1 - mn;
;         f32x2 ps2 = (f32x2){0.f, 0.f};
; #pragma unroll
;         for (int r = 0; r < 16; r += 2) { f32x2 a = (f32x2){S0[r], S0[r + 1]} + c0, bq = (f32x2){S1[r], S1[r + 1]} + c1;
;             a.x = ex2(a.x); a.y = ex2(a.y); bq.x = ex2(bq.x); bq.y = ex2(bq.y); S0[r] = a.x; S0[r + 1] = a.y; S1[r] = bq.x; S1[r + 1] = bq.y; ps2 = ps2 + a; ps2 = ps2 + bq; }
.La_qk_nodmaA:
	s_waitcnt lgkmcnt(4)
	v_mfma_f32_32x32x16_bf16 v[82:97], v[192:195], v[98:101], v[226:241]
	v_add_u32_e32 v244, s82, v168
	v_add_u32_e32 v245, s82, v169
	v_add_u32_e32 v246, s82, v170
	v_mfma_f32_32x32x16_bf16 v[82:97], v[202:205], v[102:105], v[82:97]
	v_add_u32_e32 v247, s82, v171
	v_add_f32_e32 v143, v133, v121
	v_fma_f32 v251, v127, v137, v188
	v_mfma_f32_32x32x16_bf16 v[82:97], v[210:213], v[106:109], v[82:97]
	v_fma_f32 v142, v127, v137, -v132
	v_max_f32_e32 v143, 0xff7fffff, v143
	v_add_f32_e32 v248, v142, v188
	v_mfma_f32_32x32x16_bf16 v[82:97], v[218:221], v[110:113], v[82:97]
	v_fma_f32 v255, v188, -2.0, v255
	v_add_f32_e32 v243, 4.0, v143
	ds_read_b128 v[192:195], v244 offset:16384
	ds_read_b128 v[202:205], v244 offset:20480
	ds_read_b128 v[210:213], v244 offset:24576
	ds_read_b128 v[218:221], v244 offset:28672
	s_waitcnt lgkmcnt(4)
	v_mfma_f32_32x32x16_bf16 v[66:81], v[196:199], v[98:101], v[226:241]
	v_mfma_f32_32x32x16_bf16 v[66:81], v[206:209], v[102:105], v[66:81]
	v_max3_f32 v0, v82, v83, v84
	v_max3_f32 v0, v0, v85, v86
	v_max3_f32 v0, v0, v87, v88
	v_max3_f32 v0, v0, v89, v90
	v_add_f32_e32 v82, v142, v82
	v_add_f32_e32 v83, v142, v83
	v_add_f32_e32 v84, v142, v84
	v_add_f32_e32 v85, v142, v85
	v_mfma_f32_32x32x16_bf16 v[66:81], v[214:217], v[106:109], v[66:81]
	v_add_f32_e32 v86, v142, v86
	v_add_f32_e32 v87, v142, v87
	v_add_f32_e32 v88, v142, v88
	v_add_f32_e32 v89, v142, v89
	v_exp_f32_e32 v82, v82
	v_exp_f32_e32 v83, v83
	v_exp_f32_e32 v84, v84
	v_max3_f32 v0, v0, v91, v92
	v_mfma_f32_32x32x16_bf16 v[66:81], v[222:225], v[110:113], v[66:81]
	v_exp_f32_e32 v85, v85
	v_exp_f32_e32 v86, v86
	v_exp_f32_e32 v87, v87
	v_max3_f32 v0, v0, v93, v94
	v_exp_f32_e32 v88, v88
	v_exp_f32_e32 v89, v89
	v_max3_f32 v0, v0, v95, v96
	v_max_f32_e32 v0, v0, v97
	v_cmp_ge_f32_e32 vcc, v255, v243
	s_branch .La_qk_doneA

; #define LAS __attribute__((address_space(3)))
; __device__ __forceinline__ int crow(int r, int hi) { return (r & 3) + 8 * (r >> 2) + 4 * hi; }
; __device__ __forceinline__ float ex2(float v) { return __builtin_amdgcn_exp2f(v); }
; #define MFMA32(a, b, c) __builtin_amdgcn_mfma_f32_32x32x16_bf16((a), (b), (c), 0, 0, 0)
; __device__ __forceinline__ void unit(LAS unsigned char* lds, bf16_t* P1, const bf16_t* vaT, int b, int h, int qblk, float lam, const float* subln_w, const float* khalf) {
;     ...
;         for (int ks = 0; ks < 4; ++ks) {
;             const bf16x8 a0 = *(const LAS bf16x8*)(kb + koff[ks]);
;             const bf16x8 a1 = *(const LAS bf16x8*)(kb + koff[ks] + 32 * 256);
;             S0 = MFMA32(a0, qf[ks], S0); S1 = MFMA32(a1, qf[ks], S1);
;         }
;         const int kv0 = 64 * j;
;         if (j >= NT - 2) {
; #pragma unroll
;             for (int r = 0; r < 16; ++r) { const int kv = kv0 + crow(r, hi); if (kv > qrow) S0[r] = -INFINITY; if (kv + 32 > qrow) S1[r] = -INFINITY; }
;         }
;         const float tb0 = sl2 * (float)(kv0 - qrow), tb1 = tb0 + sl2 * 32.f;
;         float mx0 = S0[0], mx1 = S1[0];
; #pragma unroll
;         for (int r = 1; r < 16; ++r) { mx0 = fmaxf(mx0, S0[r]); mx1 = fmaxf(mx1, S1[r]); }
;         float mt = fmaxf(mx0 + tb0, mx1 + tb1); mt = fmaxf(mt, __shfl_xor(mt, 32));
;         const bool skip = __all((mt < m - 24.f) || (mt == -INFINITY));
;         if (!skip) {
;         const float mn = fmaxf(m, mt); const float alpha = ex2(m - mn); m = mn;
;         const float c0 = tb0 - mn, c1 = tb1 - mn;
;         f32x2 ps2 = (f32x2){0.f, 0.f};
; #pragma unroll
;         for (int r = 0; r < 16; r += 2) { f32x2 a = (f32x2){S0[r], S0[r + 1]} + c0, bq = (f32x2){S1[r], S1[r + 1]} + c1;
;             a.x = ex2(a.x); a.y = ex2(a.y); bq.x = ex2(bq.x); bq.y = ex2(bq.y); S0[r] = a.x; S0[r + 1] = a.y; S1[r] = bq.x; S1[r + 1] = bq.y; ps2 = ps2 + a; ps2 = ps2 + bq; }
.La_qk_nodmaB:
	s_waitcnt lgkmcnt(4)
	v_mfma_f32_32x32x16_bf16 v[82:97], v[192:195], v[98:101], v[226:241]
	v_add_f32_e32 v250, 0xc2800000, v137
	v_add_f32_e32 v143, v133, v121
	v_mfma_f32_32x32x16_bf16 v[82:97], v[202:205], v[102:105], v[82:97]
	v_fma_f32 v251, v127, v250, v188
	v_fma_f32 v142, v127, v250, -v132
	v_mfma_f32_32x32x16_bf16 v[82:97], v[210:213], v[106:109], v[82:97]
	v_max_f32_e32 v143, 0xff7fffff, v143
	v_add_f32_e32 v248, v142, v188
	v_mfma_f32_32x32x16_bf16 v[82:97], v[218:221], v[110:113], v[82:97]
	v_fma_f32 v255, v188, -2.0, v255
	v_add_f32_e32 v243, 4.0, v143
	ds_read_b128 v[192:195], v244 offset:49152
	ds_read_b128 v[202:205], v244 offset:53248
	ds_read_b128 v[210:213], v244 offset:57344
	ds_read_b128 v[218:221], v244 offset:61440
	s_waitcnt lgkmcnt(4)
	v_mfma_f32_32x32x16_bf16 v[66:81], v[196:199], v[98:101], v[226:241]
	v_mfma_f32_32x32x16_bf16 v[66:81], v[206:209], v[102:105], v[66:81]
	v_max3_f32 v0, v82, v83, v84
	v_max3_f32 v0, v0, v85, v86
	v_max3_f32 v0, v0, v87, v88
	v_max3_f32 v0, v0, v89, v90
	v_add_f32_e32 v82, v142, v82
	v_add_f32_e32 v83, v142, v83
	v_add_f32_e32 v84, v142, v84
	v_add_f32_e32 v85, v142, v85
	v_mfma_f32_32x32x16_bf16 v[66:81], v[214:217], v[106:109], v[66:81]
	v_add_f32_e32 v86, v142, v86
	v_add_f32_e32 v87, v142, v87
	v_add_f32_e32 v88, v142, v88
	v_add_f32_e32 v89, v142, v89
	v_exp_f32_e32 v82, v82
	v_exp_f32_e32 v83, v83
	v_exp_f32_e32 v84, v84
	v_max3_f32 v0, v0, v91, v92
	v_mfma_f32_32x32x16_bf16 v[66:81], v[222:225], v[110:113], v[66:81]
	v_exp_f32_e32 v85, v85
	v_exp_f32_e32 v86, v86
	v_exp_f32_e32 v87, v87
	v_max3_f32 v0, v0, v93, v94
	v_exp_f32_e32 v88, v88
	v_exp_f32_e32 v89, v89
	v_max3_f32 v0, v0, v95, v96
	v_max_f32_e32 v0, v0, v97
	v_cmp_ge_f32_e32 vcc, v255, v243
	s_branch .La_qk_doneB
